# all GEMM-boundary work: fused GU + fused QKV/BIN/BGRP epilogues, hand GELU epilogue, scalar phase header (restore hazard padded)
# speedup vs baseline: 1.0214x; 1.0010x over previous
; __device__ __forceinline__ float wave_sum(float v) {
;     ...
;     for (int o = 1; o < 64; o <<= 1) v += __shfl_xor(v, o);
; __global__ void __launch_bounds__(512, 2) fwd_kernel(Args args) {
;     ...
;         const int lane = tid & 63, wave = __builtin_amdgcn_readfirstlane(tid >> 6);
;         int Gd = gridDim.x, bx = blockIdx.x; asm volatile("" : "+s"(Gd), "+s"(bx));
;         const int gw = bx * 8 + wave, NGW = Gd * 8, gtid = bx * 512 + tid, NT = Gd * 512;
.LBB0_360:
	v_mbcnt_lo_u32_b32 v225, -1, 0
	v_mbcnt_hi_u32_b32 v225, -1, v225
	v_mov_b32_e32 v224, 0x260
	v_and_b32_e32 v228, 64, v225
	v_add_u32_e32 v228, 64, v228
	v_xor_b32_e32 v229, 1, v225
	v_xor_b32_e32 v230, 2, v225
	v_xor_b32_e32 v231, 4, v225
	v_xor_b32_e32 v232, 8, v225
	v_xor_b32_e32 v233, 16, v225
	v_xor_b32_e32 v234, 32, v225
	v_mov_b32_e32 v236, 0xf149f2ca
	v_mov_b32_e32 v238, 0xfffff
	v_readlane_b32 s98, v255, 32
	s_nop 3
	v_lshl_add_u32 v172, s98, 9, v170
	s_waitcnt vmcnt(0)
	v_readlane_b32 s60, v255, 51
	s_mov_b32 s52, 0x30000
	s_movk_i32 s53, 0x2400
	s_mov_b32 s54, 0xf149f2ca
	s_mov_b64 s[56:57], 0x100000
	s_mov_b64 s[58:59], 0xfffff
	v_readlane_b32 s61, v255, 52
	s_barrier
